# nt also on the sample-MLA past-K tile LDS-DMAs (537 MB/layer stream read once), on top of prep nt loads
# baseline (speedup 1.0000x reference)
.LBB0_1077:
	s_ashr_i32 s1, s12, 3
	v_readlane_b32 s9, v255, 35
	s_add_i32 s64, s1, s9
	s_ashr_i32 s65, s64, 31
	s_and_b32 s50, s12, 7
	s_lshl_b64 s[52:53], s[64:65], 12
	s_lshl_b64 s[12:13], s[64:65], 19
	v_readlane_b32 s1, v254, 42
	s_add_u32 s60, s1, s12
	v_readlane_b32 s1, v254, 43
	s_addc_u32 s61, s1, s13
	s_lshr_b64 s[48:49], s[52:53], 5
	v_readlane_b32 s1, v254, 46
	s_or_b32 s12, s48, s50
	s_mov_b32 s13, s49
	v_or_b32_e32 v2, s1, v25
	v_and_b32_e32 v4, 0xf0, v27
	s_movk_i32 s1, 0x70
	s_lshl_b64 s[12:13], s[12:13], 17
	v_lshrrev_b32_e32 v24, 4, v2
	v_bitop3_b32 v26, v2, v4, s1 bitop3:0x6c
	v_readlane_b32 s1, v254, 47
	s_add_u32 s54, s97, s12
	s_addc_u32 s55, s0, s13
	v_or3_b32 v2, v24, s1, v26
	v_readlane_b32 s12, v253, 44
	v_lshlrev_b32_e32 v222, 4, v2
	s_barrier
	v_readlane_b32 s13, v253, 45
	v_readlane_b32 s1, v254, 56
	s_mov_b32 m0, s1
	s_nop 0
	global_load_lds_dwordx4 v222, s[54:55] nt
	s_andn2_b64 vcc, exec, s[12:13]
	v_cndmask_b32_e64 v2, 0, 1, s[12:13]
	v_cmp_ne_u32_e64 s[46:47], 1, v2
	s_cbranch_vccnz .LBB0_1079
	v_readlane_b32 s1, v254, 57
	s_mov_b32 m0, s1
	s_nop 0
	global_load_lds_dwordx4 v219, s[60:61]

.LBB0_1081:
	s_or_b64 exec, exec, s[56:57]
	s_add_u32 s12, s54, 0x2000
	s_addc_u32 s13, s55, 0
	v_readlane_b32 s9, v254, 60
	s_mov_b32 m0, s9
	s_nop 0
	global_load_lds_dwordx4 v222, s[12:13] nt
	s_and_b64 vcc, exec, s[46:47]
	s_cbranch_vccnz .LBB0_1083
	s_add_u32 s12, s60, 0x800
	s_addc_u32 s13, s61, 0
	v_readlane_b32 s9, v254, 61
	s_mov_b32 m0, s9
	s_nop 0
	global_load_lds_dwordx4 v219, s[12:13]

.LBB0_1085:
	s_or_b64 exec, exec, s[56:57]
	s_add_u32 s12, s54, 0x4000
	s_addc_u32 s13, s55, 0
	v_readlane_b32 s9, v254, 62
	s_mov_b32 m0, s9
	s_nop 0
	global_load_lds_dwordx4 v222, s[12:13] nt
	s_and_b64 vcc, exec, s[46:47]
	s_cbranch_vccnz .LBB0_1087
	s_add_u32 s12, s60, 0x1000
	s_addc_u32 s13, s61, 0
	v_readlane_b32 s9, v254, 63
	s_mov_b32 m0, s9
	s_nop 0
	global_load_lds_dwordx4 v219, s[12:13]

.LBB0_1089:
	s_or_b64 exec, exec, s[56:57]
	s_add_u32 s12, s54, 0x6000
	s_addc_u32 s13, s55, 0
	v_readlane_b32 s9, v255, 0
	s_mov_b32 m0, s9
	s_nop 0
	global_load_lds_dwordx4 v222, s[12:13] nt
	s_and_b64 vcc, exec, s[46:47]
	s_cbranch_vccnz .LBB0_1091
	s_add_u32 s12, s60, 0x1800
	s_addc_u32 s13, s61, 0
	v_readlane_b32 s9, v255, 1
	s_mov_b32 m0, s9
	s_nop 0
	global_load_lds_dwordx4 v219, s[12:13]

.LBB0_1093:
	s_or_b64 exec, exec, s[54:55]
	s_lshl_b32 s66, s64, 6
	s_add_i32 s56, s1, s92
	s_add_i32 s68, s66, 0x2000
	s_or_b32 s54, s68, s93
	s_ashr_i32 s57, s56, 31
	s_lshl_b64 s[12:13], s[64:65], 22
	v_readlane_b32 s1, v254, 38
	s_add_u32 s64, s1, s12
	v_readlane_b32 s1, v254, 39
	v_bfe_u32 v2, v214, 2, 3
	v_readlane_b32 s9, v254, 48
	s_addc_u32 s65, s1, s13
	v_readlane_b32 s1, v254, 52
	v_or_b32_e32 v4, s9, v2
	v_lshlrev_b32_e32 v28, 3, v25
	v_or_b32_e32 v5, s1, v25
	v_and_b32_e32 v224, 24, v28
	s_movk_i32 s1, 0x1a0
	v_mov_b32_e32 v6, s9
	s_mov_b32 s9, 0x3ffff3
	v_lshlrev_b32_e32 v4, 1, v4
	v_and_or_b32 v5, v5, s1, v224
	v_bitop3_b32 v6, v2, s9, v6 bitop3:0xc8
	v_and_b32_e32 v4, 8, v4
	v_readlane_b32 s1, v254, 49
	v_lshlrev_b32_e32 v5, 1, v5
	v_readlane_b32 s12, v254, 50
	v_or3_b32 v4, v6, v4, s1
	v_lshl_or_b32 v220, v4, 10, v5
	v_or_b32_e32 v4, s12, v2
	v_readlane_b32 s1, v254, 53
	v_mov_b32_e32 v6, s12
	v_lshlrev_b32_e32 v4, 1, v4
	v_or_b32_e32 v5, s1, v25
	s_movk_i32 s1, 0x1e0
	v_and_or_b32 v5, v5, s1, v224
	v_bitop3_b32 v2, v2, s9, v6 bitop3:0xc8
	v_and_b32_e32 v4, 8, v4
	v_readlane_b32 s1, v254, 51
	v_and_b32_e32 v215, 31, v214
	v_readlane_b32 s12, v254, 7
	v_or3_b32 v2, v2, v4, s1
	v_lshlrev_b32_e32 v4, 1, v5
	v_lshl_or_b32 v221, v2, 10, v4
	v_or_b32_e32 v4, s54, v215
	v_ashrrev_i32_e32 v5, 31, v4
	v_readlane_b32 s13, v254, 8
	v_lshl_add_u64 v[4:5], v[4:5], 4, s[56:57]
	s_movk_i32 s1, 0x180
	v_mov_b64_e32 v[8:9], s[12:13]
	v_lshrrev_b32_e32 v218, 5, v25
	v_mad_u64_u32 v[8:9], s[12:13], v4, s1, v[8:9]
	s_mov_b32 m0, s8
	s_nop 0
	global_load_lds_dwordx4 v220, s[64:65]
	v_mad_i32_i24 v9, v5, s1, v9
	v_lshlrev_b32_e32 v198, 4, v218
	v_mov_b32_e32 v199, v3
	s_mov_b32 m0, s38
	s_nop 0
	global_load_lds_dwordx4 v221, s[64:65]
	v_lshl_add_u64 v[4:5], v[8:9], 0, v[198:199]
	global_load_dwordx4 v[194:197], v[4:5], off
	global_load_dwordx4 v[190:193], v[4:5], off offset:32
	global_load_dwordx4 v[186:189], v[4:5], off offset:64
	global_load_dwordx4 v[182:185], v[4:5], off offset:96
	global_load_dwordx4 v[178:181], v[4:5], off offset:128
	global_load_dwordx4 v[174:177], v[4:5], off offset:160
	global_load_dwordx4 v[170:173], v[4:5], off offset:192
	global_load_dwordx4 v[166:169], v[4:5], off offset:224
	global_load_dwordx4 v[162:165], v[4:5], off offset:256
	global_load_dwordx4 v[158:161], v[4:5], off offset:288
	global_load_dwordx4 v[154:157], v[4:5], off offset:320
	global_load_dwordx4 v[150:153], v[4:5], off offset:352
	s_add_u32 s12, s64, 0x4000
	s_addc_u32 s13, s65, 0
	v_readlane_b32 s1, v255, 6
	v_readlane_b32 s16, v255, 8
	s_waitcnt vmcnt(11)
	s_waitcnt vmcnt(10)
	s_waitcnt vmcnt(9)
	s_waitcnt vmcnt(8)
	s_waitcnt vmcnt(7)
	s_waitcnt vmcnt(6)
	s_waitcnt vmcnt(5)
	s_waitcnt vmcnt(4)
	s_waitcnt vmcnt(3)
	s_waitcnt vmcnt(2)
	s_waitcnt vmcnt(1)
	s_waitcnt vmcnt(0)
	s_waitcnt vmcnt(0)
	s_barrier
	s_mov_b32 m0, s1
	s_nop 0
	global_load_lds_dwordx4 v220, s[12:13]
	v_readlane_b32 s1, v255, 7
	s_mov_b32 m0, s1
	s_nop 0
	global_load_lds_dwordx4 v221, s[12:13]
	s_add_u32 s12, s64, 0x8000
	s_addc_u32 s13, s65, 0
	s_mov_b32 m0, s10
	s_nop 0
	global_load_lds_dwordx4 v220, s[12:13]
	s_nop 0
	s_mov_b32 m0, s89
	s_nop 0
	global_load_lds_dwordx4 v221, s[12:13]
	s_and_b32 s13, s49, 0x7fff
	s_and_b32 s12, s48, 0xffffff80
	s_or_b64 s[12:13], s[12:13], s[50:51]
	s_lshl_b64 s[12:13], s[12:13], 17
	s_add_u32 s1, s97, s12
	s_addc_u32 s9, s0, s13
	s_add_u32 s12, s1, 0x8000
	s_addc_u32 s13, s9, 0
	s_mov_b32 m0, s16
	s_nop 0
	global_load_lds_dwordx4 v222, s[12:13] nt
	s_and_b64 vcc, exec, s[46:47]
	s_cbranch_vccnz .LBB0_1095
	s_add_u32 s12, s60, 0x2000
	s_addc_u32 s13, s61, 0
	v_readlane_b32 s16, v255, 9
	s_mov_b32 m0, s16
	s_nop 0
	global_load_lds_dwordx4 v219, s[12:13]

.LBB0_1097:
	s_or_b64 exec, exec, s[48:49]
	s_add_u32 s12, s1, 0xa000
	s_addc_u32 s13, s9, 0
	v_readlane_b32 s1, v255, 10
	s_mov_b32 m0, s1
	s_nop 0
	global_load_lds_dwordx4 v222, s[12:13] nt
	s_and_b64 vcc, exec, s[46:47]
	s_cbranch_vccnz .LBB0_1099
	s_add_u32 s12, s60, 0x2800
	s_addc_u32 s13, s61, 0
	v_readlane_b32 s1, v255, 11
	s_mov_b32 m0, s1
	s_nop 0
	global_load_lds_dwordx4 v219, s[12:13]

.LBB0_1126:
	s_and_b64 vcc, exec, s[70:71]
	s_cbranch_vccz .LBB0_1132
	s_lshl_b64 s[70:71], s[78:79], 4
	s_or_b64 s[72:73], s[70:71], s[52:53]
	s_lshr_b64 s[72:73], s[72:73], 5
	s_and_b32 s73, s73, 0x7fff
	s_and_b32 s72, s72, -8
	s_or_b64 s[72:73], s[72:73], s[50:51]
	s_lshl_b32 s22, s78, 13
	s_lshl_b64 s[72:73], s[72:73], 17
	s_and_b32 s23, s22, 0x18000
	s_add_u32 s72, s97, s72
	s_addc_u32 s73, s0, s73
	s_add_u32 s23, s72, s23
	s_addc_u32 s72, s73, 0
	s_and_b32 s22, s22, 0x6000
	s_add_u32 s22, s23, s22
	s_addc_u32 s23, s72, 0
	s_add_i32 s72, s40, s81
	s_add_i32 s73, s72, s84
	s_mov_b32 m0, s73
	s_nop 0
	global_load_lds_dwordx4 v222, s[22:23] nt
	s_and_b64 vcc, exec, s[46:47]
	s_cbranch_vccnz .LBB0_1129
	s_add_i32 s72, s72, s19
	s_lshl_b64 s[22:23], s[78:79], 11
	s_add_u32 s22, s60, s22
	s_addc_u32 s23, s61, s23
	s_mov_b32 m0, s72
	s_nop 0
	global_load_lds_dwordx4 v219, s[22:23]

.LBB0_1138:
	s_and_b64 vcc, exec, s[68:69]
	s_cbranch_vccz .LBB0_1144
	s_lshl_b64 s[68:69], s[78:79], 4
	s_or_b64 s[22:23], s[68:69], s[52:53]
	s_lshr_b64 s[22:23], s[22:23], 5
	s_and_b32 s23, s23, 0x7fff
	s_and_b32 s22, s22, -8
	s_or_b64 s[22:23], s[22:23], s[50:51]
	s_lshl_b32 s70, s78, 13
	s_lshl_b64 s[22:23], s[22:23], 17
	s_and_b32 s71, s70, 0x18000
	s_add_u32 s22, s97, s22
	s_addc_u32 s23, s0, s23
	s_add_u32 s22, s22, s71
	s_addc_u32 s23, s23, 0
	s_and_b32 s70, s70, 0x6000
	s_add_u32 s22, s22, s70
	s_addc_u32 s23, s23, 0
	s_add_i32 s70, s40, s81
	s_add_i32 s20, s70, s20
	s_mov_b32 m0, s20
	s_nop 0
	global_load_lds_dwordx4 v222, s[22:23] nt
	s_and_b64 vcc, exec, s[46:47]
	s_cbranch_vccnz .LBB0_1141
	s_add_i32 s70, s70, s19
	s_lshl_b64 s[22:23], s[78:79], 11
	s_add_u32 s22, s60, s22
	s_addc_u32 s23, s61, s23
	s_mov_b32 m0, s70
	s_nop 0
	global_load_lds_dwordx4 v219, s[22:23]
